# adds SADDR-form LDS-DMA loads in the main G2 K loop on top of the combined G1/G2 tile-boundary and K-loop address edits
# speedup vs baseline: 1.0099x; 1.0024x over previous
.LBB0_1369:
	s_ashr_i32 s9, s8, 31
	s_lshl_b64 s[10:11], s[8:9], 19
	v_readlane_b32 s7, v253, 15
	s_add_u32 s10, s7, s10
	v_readlane_b32 s7, v253, 16
	s_addc_u32 s11, s7, s11
	s_and_b64 s[12:13], s[38:39], exec
	s_cselect_b32 s9, s11, s15
	s_cselect_b32 s69, s10, s14
	s_ashr_i32 s7, s6, 31
	s_lshl_b64 s[12:13], s[6:7], 19
	s_add_u32 s12, s40, s12
	s_addc_u32 s13, s41, s13
	s_and_b64 s[18:19], s[38:39], exec
	s_cselect_b32 s7, s13, s17
	s_cselect_b32 s70, s12, s16
	s_add_u32 s14, s14, 0x40080
	s_addc_u32 s15, s15, 0
	s_add_u32 s71, s16, 0x100
	s_addc_u32 s74, s17, 0
	s_mov_b32 s75, -2
	s_add_u32 s16, s14, 0xfffc0080
	s_addc_u32 s17, s15, -1
	s_add_i32 s76, 0, 0x10000
	s_cmp_eq_u32 s75, 12
	s_cselect_b32 s19, s9, s17
	s_cselect_b32 s18, s69, s16
	s_cselect_b32 s17, s7, s74
	s_cselect_b32 s16, s70, s71
	s_add_i32 s80, 0, 0x14000
	v_add_u32_e32 v142, s76, v235
	v_add_u32_e32 v158, s80, v235
	ds_read_b128 v[130:133], v142
	ds_read_b128 v[134:137], v142 offset:1024
	ds_read_b128 v[138:141], v142 offset:2048
	ds_read_b128 v[142:145], v142 offset:3072
	ds_read_b128 v[146:149], v158
	ds_read_b128 v[150:153], v158 offset:1024
	ds_read_b128 v[154:157], v158 offset:2048
	ds_read_b128 v[158:161], v158 offset:3072
	s_add_i32 m0, s21, 0xc000
	ds_read_b128 v[162:165], v237
	ds_read_b128 v[166:169], v237 offset:1024
	ds_read_b128 v[170:173], v237 offset:2048
	ds_read_b128 v[174:177], v237 offset:3072
	ds_read_b128 v[178:181], v237 offset:4096
	ds_read_b128 v[182:185], v237 offset:5120
	ds_read_b128 v[186:189], v237 offset:6144
	ds_read_b128 v[210:213], v237 offset:7168
	global_load_lds_dwordx4 v206, s[14:15]
	s_add_i32 m0, s21, 0xe000
	s_nop 0
	global_load_lds_dwordx4 v208, s[14:15]
	s_waitcnt vmcnt(8)
	s_waitcnt lgkmcnt(0)
	s_barrier
	s_setprio 1
	s_waitcnt lgkmcnt(0)
	v_mfma_f32_16x16x32_bf16 v[126:129], v[130:133], v[162:165], 0
	v_mfma_f32_16x16x32_bf16 v[122:125], v[138:141], v[162:165], 0
	v_mfma_f32_16x16x32_bf16 v[114:117], v[130:133], v[170:173], 0
	v_mfma_f32_16x16x32_bf16 v[106:109], v[138:141], v[170:173], 0
	v_mfma_f32_16x16x32_bf16 v[98:101], v[130:133], v[178:181], 0
	v_mfma_f32_16x16x32_bf16 v[90:93], v[138:141], v[178:181], 0
	v_mfma_f32_16x16x32_bf16 v[82:85], v[130:133], v[186:189], 0
	v_mfma_f32_16x16x32_bf16 v[74:77], v[138:141], v[186:189], 0
	v_mfma_f32_16x16x32_bf16 v[126:129], v[134:137], v[166:169], v[126:129]
	v_mfma_f32_16x16x32_bf16 v[122:125], v[142:145], v[166:169], v[122:125]
	v_mfma_f32_16x16x32_bf16 v[114:117], v[134:137], v[174:177], v[114:117]
	v_mfma_f32_16x16x32_bf16 v[106:109], v[142:145], v[174:177], v[106:109]
	v_mfma_f32_16x16x32_bf16 v[98:101], v[134:137], v[182:185], v[98:101]
	v_mfma_f32_16x16x32_bf16 v[90:93], v[142:145], v[182:185], v[90:93]
	v_mfma_f32_16x16x32_bf16 v[82:85], v[134:137], v[210:213], v[82:85]
	v_mfma_f32_16x16x32_bf16 v[74:77], v[142:145], v[210:213], v[74:77]
	s_setprio 0
	s_setprio 1
	v_mfma_f32_16x16x32_bf16 v[118:121], v[146:149], v[162:165], 0
	v_mfma_f32_16x16x32_bf16 v[110:113], v[154:157], v[162:165], 0
	v_mfma_f32_16x16x32_bf16 v[102:105], v[146:149], v[170:173], 0
	v_mfma_f32_16x16x32_bf16 v[94:97], v[154:157], v[170:173], 0
	v_mfma_f32_16x16x32_bf16 v[86:89], v[146:149], v[178:181], 0
	v_mfma_f32_16x16x32_bf16 v[78:81], v[154:157], v[178:181], 0
	v_mfma_f32_16x16x32_bf16 v[70:73], v[146:149], v[186:189], 0
	v_mfma_f32_16x16x32_bf16 v[66:69], v[154:157], v[186:189], 0
	v_mfma_f32_16x16x32_bf16 v[118:121], v[150:153], v[166:169], v[118:121]
	v_mfma_f32_16x16x32_bf16 v[110:113], v[158:161], v[166:169], v[110:113]
	v_mfma_f32_16x16x32_bf16 v[102:105], v[150:153], v[174:177], v[102:105]
	v_mfma_f32_16x16x32_bf16 v[94:97], v[158:161], v[174:177], v[94:97]
	v_mfma_f32_16x16x32_bf16 v[86:89], v[150:153], v[182:185], v[86:89]
	v_mfma_f32_16x16x32_bf16 v[78:81], v[158:161], v[182:185], v[78:81]
	v_mfma_f32_16x16x32_bf16 v[70:73], v[150:153], v[210:213], v[70:73]
	v_mfma_f32_16x16x32_bf16 v[66:69], v[158:161], v[210:213], v[66:69]
	s_setprio 0
	s_barrier
	s_add_i32 s76, s76, s20
	s_mov_b32 m0, s76
	ds_read_b128 v[162:165], v237 offset:16384
	ds_read_b128 v[166:169], v237 offset:17408
	ds_read_b128 v[170:173], v237 offset:18432
	ds_read_b128 v[174:177], v237 offset:19456
	ds_read_b128 v[178:181], v237 offset:20480
	ds_read_b128 v[182:185], v237 offset:21504
	ds_read_b128 v[186:189], v237 offset:22528
	ds_read_b128 v[210:213], v237 offset:23552
	global_load_lds_dwordx4 v202, s[16:17]
	s_add_i32 m0, s76, 0x2000
	s_add_u32 s98, s18, s48
	s_addc_u32 s99, s19, s49
	s_add_u32 s76, s16, 0x40000
	s_addc_u32 s77, s17, 0
	s_add_i32 s80, s80, s20
	global_load_lds_dwordx4 v198, s[16:17]
	s_mov_b32 m0, s80
	s_nop 0
	global_load_lds_dwordx4 v202, s[76:77]
	s_add_i32 m0, s80, 0x2000
	s_nop 0
	global_load_lds_dwordx4 v198, s[76:77]
	s_mov_b32 m0, s21
	s_nop 0
	global_load_lds_dwordx4 v204, s[18:19]
	s_mov_b32 m0, s25
	s_nop 0
	global_load_lds_dwordx4 v200, s[18:19]
	s_waitcnt vmcnt(8)
	s_waitcnt lgkmcnt(0)
	s_barrier
	s_setprio 1
	s_waitcnt lgkmcnt(0)
	v_mfma_f32_16x16x32_bf16 v[62:65], v[130:133], v[162:165], 0
	v_mfma_f32_16x16x32_bf16 v[58:61], v[138:141], v[162:165], 0
	v_mfma_f32_16x16x32_bf16 v[50:53], v[130:133], v[170:173], 0
	v_mfma_f32_16x16x32_bf16 v[42:45], v[138:141], v[170:173], 0
	v_mfma_f32_16x16x32_bf16 v[34:37], v[130:133], v[178:181], 0
	v_mfma_f32_16x16x32_bf16 v[26:29], v[138:141], v[178:181], 0
	v_mfma_f32_16x16x32_bf16 v[18:21], v[130:133], v[186:189], 0
	v_mfma_f32_16x16x32_bf16 v[10:13], v[138:141], v[186:189], 0
	v_mfma_f32_16x16x32_bf16 v[62:65], v[134:137], v[166:169], v[62:65]
	v_mfma_f32_16x16x32_bf16 v[58:61], v[142:145], v[166:169], v[58:61]
	v_mfma_f32_16x16x32_bf16 v[50:53], v[134:137], v[174:177], v[50:53]
	v_mfma_f32_16x16x32_bf16 v[42:45], v[142:145], v[174:177], v[42:45]
	v_mfma_f32_16x16x32_bf16 v[34:37], v[134:137], v[182:185], v[34:37]
	v_mfma_f32_16x16x32_bf16 v[26:29], v[142:145], v[182:185], v[26:29]
	v_mfma_f32_16x16x32_bf16 v[18:21], v[134:137], v[210:213], v[18:21]
	v_mfma_f32_16x16x32_bf16 v[10:13], v[142:145], v[210:213], v[10:13]
	s_setprio 0
	s_setprio 1
	v_mfma_f32_16x16x32_bf16 v[54:57], v[146:149], v[162:165], 0
	v_mfma_f32_16x16x32_bf16 v[46:49], v[154:157], v[162:165], 0
	v_mfma_f32_16x16x32_bf16 v[38:41], v[146:149], v[170:173], 0
	v_mfma_f32_16x16x32_bf16 v[30:33], v[154:157], v[170:173], 0
	v_mfma_f32_16x16x32_bf16 v[22:25], v[146:149], v[178:181], 0
	v_mfma_f32_16x16x32_bf16 v[14:17], v[154:157], v[178:181], 0
	v_mfma_f32_16x16x32_bf16 v[6:9], v[146:149], v[186:189], 0
	v_mfma_f32_16x16x32_bf16 v[2:5], v[154:157], v[186:189], 0
	v_mfma_f32_16x16x32_bf16 v[54:57], v[150:153], v[166:169], v[54:57]
	v_mfma_f32_16x16x32_bf16 v[46:49], v[158:161], v[166:169], v[46:49]
	v_mfma_f32_16x16x32_bf16 v[38:41], v[150:153], v[174:177], v[38:41]
	v_mfma_f32_16x16x32_bf16 v[30:33], v[158:161], v[174:177], v[30:33]
	v_mfma_f32_16x16x32_bf16 v[22:25], v[150:153], v[182:185], v[22:25]
	v_mfma_f32_16x16x32_bf16 v[14:17], v[158:161], v[182:185], v[14:17]
	v_mfma_f32_16x16x32_bf16 v[6:9], v[150:153], v[210:213], v[6:9]
	v_mfma_f32_16x16x32_bf16 v[2:5], v[158:161], v[210:213], v[2:5]
	s_setprio 0
	s_barrier
	s_add_i32 s76, 0, 0x18000
	s_add_i32 s77, 0, 0x1c000
	v_add_u32_e32 v142, s76, v235
	v_add_u32_e32 v158, s77, v235
	ds_read_b128 v[130:133], v142
	ds_read_b128 v[134:137], v142 offset:1024
	ds_read_b128 v[138:141], v142 offset:2048
	ds_read_b128 v[142:145], v142 offset:3072
	ds_read_b128 v[146:149], v158
	ds_read_b128 v[150:153], v158 offset:1024
	ds_read_b128 v[154:157], v158 offset:2048
	ds_read_b128 v[158:161], v158 offset:3072
	s_add_u32 s18, s18, 0x40000
	s_addc_u32 s19, s19, 0
	s_mov_b32 m0, s42
	ds_read_b128 v[162:165], v237 offset:32768
	ds_read_b128 v[166:169], v237 offset:33792
	ds_read_b128 v[170:173], v237 offset:34816
	ds_read_b128 v[174:177], v237 offset:35840
	ds_read_b128 v[178:181], v237 offset:36864
	ds_read_b128 v[182:185], v237 offset:37888
	ds_read_b128 v[186:189], v237 offset:38912
	ds_read_b128 v[210:213], v237 offset:39936
	global_load_lds_dwordx4 v204, s[18:19]
	s_mov_b32 m0, s43
	s_nop 0
	global_load_lds_dwordx4 v200, s[18:19]
	s_waitcnt vmcnt(8)
	s_waitcnt lgkmcnt(0)
	s_barrier
	s_setprio 1
	s_waitcnt lgkmcnt(0)
	v_mfma_f32_16x16x32_bf16 v[126:129], v[130:133], v[162:165], v[126:129]
	v_mfma_f32_16x16x32_bf16 v[122:125], v[138:141], v[162:165], v[122:125]
	v_mfma_f32_16x16x32_bf16 v[114:117], v[130:133], v[170:173], v[114:117]
	v_mfma_f32_16x16x32_bf16 v[106:109], v[138:141], v[170:173], v[106:109]
	v_mfma_f32_16x16x32_bf16 v[98:101], v[130:133], v[178:181], v[98:101]
	v_mfma_f32_16x16x32_bf16 v[90:93], v[138:141], v[178:181], v[90:93]
	v_mfma_f32_16x16x32_bf16 v[82:85], v[130:133], v[186:189], v[82:85]
	v_mfma_f32_16x16x32_bf16 v[74:77], v[138:141], v[186:189], v[74:77]
	v_mfma_f32_16x16x32_bf16 v[126:129], v[134:137], v[166:169], v[126:129]
	v_mfma_f32_16x16x32_bf16 v[122:125], v[142:145], v[166:169], v[122:125]
	v_mfma_f32_16x16x32_bf16 v[114:117], v[134:137], v[174:177], v[114:117]
	v_mfma_f32_16x16x32_bf16 v[106:109], v[142:145], v[174:177], v[106:109]
	v_mfma_f32_16x16x32_bf16 v[98:101], v[134:137], v[182:185], v[98:101]
	v_mfma_f32_16x16x32_bf16 v[90:93], v[142:145], v[182:185], v[90:93]
	v_mfma_f32_16x16x32_bf16 v[82:85], v[134:137], v[210:213], v[82:85]
	v_mfma_f32_16x16x32_bf16 v[74:77], v[142:145], v[210:213], v[74:77]
	s_setprio 0
	s_setprio 1
	v_mfma_f32_16x16x32_bf16 v[118:121], v[146:149], v[162:165], v[118:121]
	v_mfma_f32_16x16x32_bf16 v[110:113], v[154:157], v[162:165], v[110:113]
	v_mfma_f32_16x16x32_bf16 v[102:105], v[146:149], v[170:173], v[102:105]
	v_mfma_f32_16x16x32_bf16 v[94:97], v[154:157], v[170:173], v[94:97]
	v_mfma_f32_16x16x32_bf16 v[86:89], v[146:149], v[178:181], v[86:89]
	v_mfma_f32_16x16x32_bf16 v[78:81], v[154:157], v[178:181], v[78:81]
	v_mfma_f32_16x16x32_bf16 v[70:73], v[146:149], v[186:189], v[70:73]
	v_mfma_f32_16x16x32_bf16 v[66:69], v[154:157], v[186:189], v[66:69]
	v_mfma_f32_16x16x32_bf16 v[118:121], v[150:153], v[166:169], v[118:121]
	v_mfma_f32_16x16x32_bf16 v[110:113], v[158:161], v[166:169], v[110:113]
	v_mfma_f32_16x16x32_bf16 v[102:105], v[150:153], v[174:177], v[102:105]
	v_mfma_f32_16x16x32_bf16 v[94:97], v[158:161], v[174:177], v[94:97]
	v_mfma_f32_16x16x32_bf16 v[86:89], v[150:153], v[182:185], v[86:89]
	v_mfma_f32_16x16x32_bf16 v[78:81], v[158:161], v[182:185], v[78:81]
	v_mfma_f32_16x16x32_bf16 v[70:73], v[150:153], v[210:213], v[70:73]
	v_mfma_f32_16x16x32_bf16 v[66:69], v[158:161], v[210:213], v[66:69]
	s_setprio 0
	s_barrier
	s_add_i32 s18, s76, s20
	s_add_u32 vcc_lo, s16, s48
	s_addc_u32 vcc_hi, s17, s49
	s_mov_b32 m0, s18
	ds_read_b128 v[162:165], v237 offset:49152
	ds_read_b128 v[166:169], v237 offset:50176
	ds_read_b128 v[170:173], v237 offset:51200
	ds_read_b128 v[174:177], v237 offset:52224
	ds_read_b128 v[178:181], v237 offset:53248
	ds_read_b128 v[182:185], v237 offset:54272
	ds_read_b128 v[186:189], v237 offset:55296
	ds_read_b128 v[210:213], v237 offset:56320
	global_load_lds_dwordx4 v202, vcc
	s_add_i32 m0, s18, 0x2000
	s_add_u32 s16, s16, 0x40080
	s_addc_u32 s17, s17, 0
	s_add_i32 s18, s77, s20
	global_load_lds_dwordx4 v198, vcc
	s_mov_b32 m0, s18
	s_nop 0
	global_load_lds_dwordx4 v202, s[16:17]
	s_add_i32 m0, s18, 0x2000
	s_nop 0
	global_load_lds_dwordx4 v198, s[16:17]
	s_mov_b32 m0, s44
	s_nop 0
	global_load_lds_dwordx4 v204, s[98:99]
	s_mov_b32 m0, s45
	s_nop 0
	global_load_lds_dwordx4 v200, s[98:99]
	s_waitcnt vmcnt(8)
	s_waitcnt lgkmcnt(0)
	s_barrier
	s_setprio 1
	s_waitcnt lgkmcnt(0)
	v_mfma_f32_16x16x32_bf16 v[62:65], v[130:133], v[162:165], v[62:65]
	v_mfma_f32_16x16x32_bf16 v[58:61], v[138:141], v[162:165], v[58:61]
	v_mfma_f32_16x16x32_bf16 v[50:53], v[130:133], v[170:173], v[50:53]
	v_mfma_f32_16x16x32_bf16 v[42:45], v[138:141], v[170:173], v[42:45]
	v_mfma_f32_16x16x32_bf16 v[34:37], v[130:133], v[178:181], v[34:37]
	v_mfma_f32_16x16x32_bf16 v[26:29], v[138:141], v[178:181], v[26:29]
	v_mfma_f32_16x16x32_bf16 v[18:21], v[130:133], v[186:189], v[18:21]
	v_mfma_f32_16x16x32_bf16 v[10:13], v[138:141], v[186:189], v[10:13]
	v_mfma_f32_16x16x32_bf16 v[62:65], v[134:137], v[166:169], v[62:65]
	v_mfma_f32_16x16x32_bf16 v[58:61], v[142:145], v[166:169], v[58:61]
	v_mfma_f32_16x16x32_bf16 v[50:53], v[134:137], v[174:177], v[50:53]
	v_mfma_f32_16x16x32_bf16 v[42:45], v[142:145], v[174:177], v[42:45]
	v_mfma_f32_16x16x32_bf16 v[34:37], v[134:137], v[182:185], v[34:37]
	v_mfma_f32_16x16x32_bf16 v[26:29], v[142:145], v[182:185], v[26:29]
	v_mfma_f32_16x16x32_bf16 v[18:21], v[134:137], v[210:213], v[18:21]
	v_mfma_f32_16x16x32_bf16 v[10:13], v[142:145], v[210:213], v[10:13]
	s_setprio 0
	s_setprio 1
	v_mfma_f32_16x16x32_bf16 v[54:57], v[146:149], v[162:165], v[54:57]
	v_mfma_f32_16x16x32_bf16 v[46:49], v[154:157], v[162:165], v[46:49]
	v_mfma_f32_16x16x32_bf16 v[38:41], v[146:149], v[170:173], v[38:41]
	v_mfma_f32_16x16x32_bf16 v[30:33], v[154:157], v[170:173], v[30:33]
	v_mfma_f32_16x16x32_bf16 v[22:25], v[146:149], v[178:181], v[22:25]
	v_mfma_f32_16x16x32_bf16 v[14:17], v[154:157], v[178:181], v[14:17]
	v_mfma_f32_16x16x32_bf16 v[6:9], v[146:149], v[186:189], v[6:9]
	v_mfma_f32_16x16x32_bf16 v[2:5], v[154:157], v[186:189], v[2:5]
	v_mfma_f32_16x16x32_bf16 v[54:57], v[150:153], v[166:169], v[54:57]
	v_mfma_f32_16x16x32_bf16 v[46:49], v[158:161], v[166:169], v[46:49]
	v_mfma_f32_16x16x32_bf16 v[38:41], v[150:153], v[174:177], v[38:41]
	v_mfma_f32_16x16x32_bf16 v[30:33], v[158:161], v[174:177], v[30:33]
	v_mfma_f32_16x16x32_bf16 v[22:25], v[150:153], v[182:185], v[22:25]
	v_mfma_f32_16x16x32_bf16 v[14:17], v[158:161], v[182:185], v[14:17]
	v_mfma_f32_16x16x32_bf16 v[6:9], v[150:153], v[210:213], v[6:9]
	v_mfma_f32_16x16x32_bf16 v[2:5], v[158:161], v[210:213], v[2:5]
	s_setprio 0
	s_barrier
	s_add_i32 s75, s75, 2
	s_add_u32 s14, s14, 0x100
	s_addc_u32 s15, s15, 0
	s_add_u32 s71, s71, 0x100
	s_addc_u32 s74, s74, 0
	s_cmp_gt_u32 s75, 13
	s_cbranch_scc0 .LBB0_1370
.LBB0_1370:
	s_add_u32 s16, s14, 0xfffc0080
	s_addc_u32 s17, s15, -1
	s_add_i32 s76, 0, 0x10000
	s_cmp_eq_u32 s75, 12
	s_cselect_b32 s19, s9, s17
	s_cselect_b32 s18, s69, s16
	s_cselect_b32 s17, s7, s74
	s_cselect_b32 s16, s70, s71
	s_add_i32 s80, 0, 0x14000
	v_add_u32_e32 v142, s76, v235
	v_add_u32_e32 v158, s80, v235
	ds_read_b128 v[130:133], v142
	ds_read_b128 v[134:137], v142 offset:1024
	ds_read_b128 v[138:141], v142 offset:2048
	ds_read_b128 v[142:145], v142 offset:3072
	ds_read_b128 v[146:149], v158
	ds_read_b128 v[150:153], v158 offset:1024
	ds_read_b128 v[154:157], v158 offset:2048
	ds_read_b128 v[158:161], v158 offset:3072
	s_add_i32 m0, s21, 0xc000
	ds_read_b128 v[162:165], v237
	ds_read_b128 v[166:169], v237 offset:1024
	ds_read_b128 v[170:173], v237 offset:2048
	ds_read_b128 v[174:177], v237 offset:3072
	ds_read_b128 v[178:181], v237 offset:4096
	ds_read_b128 v[182:185], v237 offset:5120
	ds_read_b128 v[186:189], v237 offset:6144
	ds_read_b128 v[210:213], v237 offset:7168
	global_load_lds_dwordx4 v206, s[14:15]
	s_add_i32 m0, s21, 0xe000
	s_nop 0
	global_load_lds_dwordx4 v208, s[14:15]
	s_waitcnt vmcnt(8)
	s_waitcnt lgkmcnt(0)
	s_barrier
	s_setprio 1
	s_waitcnt lgkmcnt(0)
	v_mfma_f32_16x16x32_bf16 v[126:129], v[130:133], v[162:165], v[126:129]
	v_mfma_f32_16x16x32_bf16 v[122:125], v[138:141], v[162:165], v[122:125]
	v_mfma_f32_16x16x32_bf16 v[114:117], v[130:133], v[170:173], v[114:117]
	v_mfma_f32_16x16x32_bf16 v[106:109], v[138:141], v[170:173], v[106:109]
	v_mfma_f32_16x16x32_bf16 v[98:101], v[130:133], v[178:181], v[98:101]
	v_mfma_f32_16x16x32_bf16 v[90:93], v[138:141], v[178:181], v[90:93]
	v_mfma_f32_16x16x32_bf16 v[82:85], v[130:133], v[186:189], v[82:85]
	v_mfma_f32_16x16x32_bf16 v[74:77], v[138:141], v[186:189], v[74:77]
	v_mfma_f32_16x16x32_bf16 v[126:129], v[134:137], v[166:169], v[126:129]
	v_mfma_f32_16x16x32_bf16 v[122:125], v[142:145], v[166:169], v[122:125]
	v_mfma_f32_16x16x32_bf16 v[114:117], v[134:137], v[174:177], v[114:117]
	v_mfma_f32_16x16x32_bf16 v[106:109], v[142:145], v[174:177], v[106:109]
	v_mfma_f32_16x16x32_bf16 v[98:101], v[134:137], v[182:185], v[98:101]
	v_mfma_f32_16x16x32_bf16 v[90:93], v[142:145], v[182:185], v[90:93]
	v_mfma_f32_16x16x32_bf16 v[82:85], v[134:137], v[210:213], v[82:85]
	v_mfma_f32_16x16x32_bf16 v[74:77], v[142:145], v[210:213], v[74:77]
	s_setprio 0
	s_setprio 1
	v_mfma_f32_16x16x32_bf16 v[118:121], v[146:149], v[162:165], v[118:121]
	v_mfma_f32_16x16x32_bf16 v[110:113], v[154:157], v[162:165], v[110:113]
	v_mfma_f32_16x16x32_bf16 v[102:105], v[146:149], v[170:173], v[102:105]
	v_mfma_f32_16x16x32_bf16 v[94:97], v[154:157], v[170:173], v[94:97]
	v_mfma_f32_16x16x32_bf16 v[86:89], v[146:149], v[178:181], v[86:89]
	v_mfma_f32_16x16x32_bf16 v[78:81], v[154:157], v[178:181], v[78:81]
	v_mfma_f32_16x16x32_bf16 v[70:73], v[146:149], v[186:189], v[70:73]
	v_mfma_f32_16x16x32_bf16 v[66:69], v[154:157], v[186:189], v[66:69]
	v_mfma_f32_16x16x32_bf16 v[118:121], v[150:153], v[166:169], v[118:121]
	v_mfma_f32_16x16x32_bf16 v[110:113], v[158:161], v[166:169], v[110:113]
	v_mfma_f32_16x16x32_bf16 v[102:105], v[150:153], v[174:177], v[102:105]
	v_mfma_f32_16x16x32_bf16 v[94:97], v[158:161], v[174:177], v[94:97]
	v_mfma_f32_16x16x32_bf16 v[86:89], v[150:153], v[182:185], v[86:89]
	v_mfma_f32_16x16x32_bf16 v[78:81], v[158:161], v[182:185], v[78:81]
	v_mfma_f32_16x16x32_bf16 v[70:73], v[150:153], v[210:213], v[70:73]
	v_mfma_f32_16x16x32_bf16 v[66:69], v[158:161], v[210:213], v[66:69]
	s_setprio 0
	s_barrier
	s_add_i32 s76, s76, s20
	s_mov_b32 m0, s76
	ds_read_b128 v[162:165], v237 offset:16384
	ds_read_b128 v[166:169], v237 offset:17408
	ds_read_b128 v[170:173], v237 offset:18432
	ds_read_b128 v[174:177], v237 offset:19456
	ds_read_b128 v[178:181], v237 offset:20480
	ds_read_b128 v[182:185], v237 offset:21504
	ds_read_b128 v[186:189], v237 offset:22528
	ds_read_b128 v[210:213], v237 offset:23552
	global_load_lds_dwordx4 v202, s[16:17]
	s_add_i32 m0, s76, 0x2000
	s_add_u32 s98, s18, s48
	s_addc_u32 s99, s19, s49
	s_add_u32 s76, s16, 0x40000
	s_addc_u32 s77, s17, 0
	s_add_i32 s80, s80, s20
	global_load_lds_dwordx4 v198, s[16:17]
	s_mov_b32 m0, s80
	s_nop 0
	global_load_lds_dwordx4 v202, s[76:77]
	s_add_i32 m0, s80, 0x2000
	s_nop 0
	global_load_lds_dwordx4 v198, s[76:77]
	s_mov_b32 m0, s21
	s_nop 0
	global_load_lds_dwordx4 v204, s[18:19]
	s_mov_b32 m0, s25
	s_nop 0
	global_load_lds_dwordx4 v200, s[18:19]
	s_waitcnt vmcnt(8)
	s_waitcnt lgkmcnt(0)
	s_barrier
	s_setprio 1
	s_waitcnt lgkmcnt(0)
	v_mfma_f32_16x16x32_bf16 v[62:65], v[130:133], v[162:165], v[62:65]
	v_mfma_f32_16x16x32_bf16 v[58:61], v[138:141], v[162:165], v[58:61]
	v_mfma_f32_16x16x32_bf16 v[50:53], v[130:133], v[170:173], v[50:53]
	v_mfma_f32_16x16x32_bf16 v[42:45], v[138:141], v[170:173], v[42:45]
	v_mfma_f32_16x16x32_bf16 v[34:37], v[130:133], v[178:181], v[34:37]
	v_mfma_f32_16x16x32_bf16 v[26:29], v[138:141], v[178:181], v[26:29]
	v_mfma_f32_16x16x32_bf16 v[18:21], v[130:133], v[186:189], v[18:21]
	v_mfma_f32_16x16x32_bf16 v[10:13], v[138:141], v[186:189], v[10:13]
	v_mfma_f32_16x16x32_bf16 v[62:65], v[134:137], v[166:169], v[62:65]
	v_mfma_f32_16x16x32_bf16 v[58:61], v[142:145], v[166:169], v[58:61]
	v_mfma_f32_16x16x32_bf16 v[50:53], v[134:137], v[174:177], v[50:53]
	v_mfma_f32_16x16x32_bf16 v[42:45], v[142:145], v[174:177], v[42:45]
	v_mfma_f32_16x16x32_bf16 v[34:37], v[134:137], v[182:185], v[34:37]
	v_mfma_f32_16x16x32_bf16 v[26:29], v[142:145], v[182:185], v[26:29]
	v_mfma_f32_16x16x32_bf16 v[18:21], v[134:137], v[210:213], v[18:21]
	v_mfma_f32_16x16x32_bf16 v[10:13], v[142:145], v[210:213], v[10:13]
	s_setprio 0
	s_setprio 1
	v_mfma_f32_16x16x32_bf16 v[54:57], v[146:149], v[162:165], v[54:57]
	v_mfma_f32_16x16x32_bf16 v[46:49], v[154:157], v[162:165], v[46:49]
	v_mfma_f32_16x16x32_bf16 v[38:41], v[146:149], v[170:173], v[38:41]
	v_mfma_f32_16x16x32_bf16 v[30:33], v[154:157], v[170:173], v[30:33]
	v_mfma_f32_16x16x32_bf16 v[22:25], v[146:149], v[178:181], v[22:25]
	v_mfma_f32_16x16x32_bf16 v[14:17], v[154:157], v[178:181], v[14:17]
	v_mfma_f32_16x16x32_bf16 v[6:9], v[146:149], v[186:189], v[6:9]
	v_mfma_f32_16x16x32_bf16 v[2:5], v[154:157], v[186:189], v[2:5]
	v_mfma_f32_16x16x32_bf16 v[54:57], v[150:153], v[166:169], v[54:57]
	v_mfma_f32_16x16x32_bf16 v[46:49], v[158:161], v[166:169], v[46:49]
	v_mfma_f32_16x16x32_bf16 v[38:41], v[150:153], v[174:177], v[38:41]
	v_mfma_f32_16x16x32_bf16 v[30:33], v[158:161], v[174:177], v[30:33]
	v_mfma_f32_16x16x32_bf16 v[22:25], v[150:153], v[182:185], v[22:25]
	v_mfma_f32_16x16x32_bf16 v[14:17], v[158:161], v[182:185], v[14:17]
	v_mfma_f32_16x16x32_bf16 v[6:9], v[150:153], v[210:213], v[6:9]
	v_mfma_f32_16x16x32_bf16 v[2:5], v[158:161], v[210:213], v[2:5]
	s_setprio 0
	s_barrier
	s_add_i32 s76, 0, 0x18000
	s_add_i32 s77, 0, 0x1c000
	v_add_u32_e32 v142, s76, v235
	v_add_u32_e32 v158, s77, v235
	ds_read_b128 v[130:133], v142
	ds_read_b128 v[134:137], v142 offset:1024
	ds_read_b128 v[138:141], v142 offset:2048
	ds_read_b128 v[142:145], v142 offset:3072
	ds_read_b128 v[146:149], v158
	ds_read_b128 v[150:153], v158 offset:1024
	ds_read_b128 v[154:157], v158 offset:2048
	ds_read_b128 v[158:161], v158 offset:3072
	s_add_u32 s18, s18, 0x40000
	s_addc_u32 s19, s19, 0
	s_mov_b32 m0, s42
	ds_read_b128 v[162:165], v237 offset:32768
	ds_read_b128 v[166:169], v237 offset:33792
	ds_read_b128 v[170:173], v237 offset:34816
	ds_read_b128 v[174:177], v237 offset:35840
	ds_read_b128 v[178:181], v237 offset:36864
	ds_read_b128 v[182:185], v237 offset:37888
	ds_read_b128 v[186:189], v237 offset:38912
	ds_read_b128 v[210:213], v237 offset:39936
	global_load_lds_dwordx4 v204, s[18:19]
	s_mov_b32 m0, s43
	s_nop 0
	global_load_lds_dwordx4 v200, s[18:19]
	s_waitcnt vmcnt(8)
	s_waitcnt lgkmcnt(0)
	s_barrier
	s_setprio 1
	s_waitcnt lgkmcnt(0)
	v_mfma_f32_16x16x32_bf16 v[126:129], v[130:133], v[162:165], v[126:129]
	v_mfma_f32_16x16x32_bf16 v[122:125], v[138:141], v[162:165], v[122:125]
	v_mfma_f32_16x16x32_bf16 v[114:117], v[130:133], v[170:173], v[114:117]
	v_mfma_f32_16x16x32_bf16 v[106:109], v[138:141], v[170:173], v[106:109]
	v_mfma_f32_16x16x32_bf16 v[98:101], v[130:133], v[178:181], v[98:101]
	v_mfma_f32_16x16x32_bf16 v[90:93], v[138:141], v[178:181], v[90:93]
	v_mfma_f32_16x16x32_bf16 v[82:85], v[130:133], v[186:189], v[82:85]
	v_mfma_f32_16x16x32_bf16 v[74:77], v[138:141], v[186:189], v[74:77]
	v_mfma_f32_16x16x32_bf16 v[126:129], v[134:137], v[166:169], v[126:129]
	v_mfma_f32_16x16x32_bf16 v[122:125], v[142:145], v[166:169], v[122:125]
	v_mfma_f32_16x16x32_bf16 v[114:117], v[134:137], v[174:177], v[114:117]
	v_mfma_f32_16x16x32_bf16 v[106:109], v[142:145], v[174:177], v[106:109]
	v_mfma_f32_16x16x32_bf16 v[98:101], v[134:137], v[182:185], v[98:101]
	v_mfma_f32_16x16x32_bf16 v[90:93], v[142:145], v[182:185], v[90:93]
	v_mfma_f32_16x16x32_bf16 v[82:85], v[134:137], v[210:213], v[82:85]
	v_mfma_f32_16x16x32_bf16 v[74:77], v[142:145], v[210:213], v[74:77]
	s_setprio 0
	s_setprio 1
	v_mfma_f32_16x16x32_bf16 v[118:121], v[146:149], v[162:165], v[118:121]
	v_mfma_f32_16x16x32_bf16 v[110:113], v[154:157], v[162:165], v[110:113]
	v_mfma_f32_16x16x32_bf16 v[102:105], v[146:149], v[170:173], v[102:105]
	v_mfma_f32_16x16x32_bf16 v[94:97], v[154:157], v[170:173], v[94:97]
	v_mfma_f32_16x16x32_bf16 v[86:89], v[146:149], v[178:181], v[86:89]
	v_mfma_f32_16x16x32_bf16 v[78:81], v[154:157], v[178:181], v[78:81]
	v_mfma_f32_16x16x32_bf16 v[70:73], v[146:149], v[186:189], v[70:73]
	v_mfma_f32_16x16x32_bf16 v[66:69], v[154:157], v[186:189], v[66:69]
	v_mfma_f32_16x16x32_bf16 v[118:121], v[150:153], v[166:169], v[118:121]
	v_mfma_f32_16x16x32_bf16 v[110:113], v[158:161], v[166:169], v[110:113]
	v_mfma_f32_16x16x32_bf16 v[102:105], v[150:153], v[174:177], v[102:105]
	v_mfma_f32_16x16x32_bf16 v[94:97], v[158:161], v[174:177], v[94:97]
	v_mfma_f32_16x16x32_bf16 v[86:89], v[150:153], v[182:185], v[86:89]
	v_mfma_f32_16x16x32_bf16 v[78:81], v[158:161], v[182:185], v[78:81]
	v_mfma_f32_16x16x32_bf16 v[70:73], v[150:153], v[210:213], v[70:73]
	v_mfma_f32_16x16x32_bf16 v[66:69], v[158:161], v[210:213], v[66:69]
	s_setprio 0
	s_barrier
	s_add_i32 s18, s76, s20
	s_add_u32 vcc_lo, s16, s48
	s_addc_u32 vcc_hi, s17, s49
	s_mov_b32 m0, s18
	ds_read_b128 v[162:165], v237 offset:49152
	ds_read_b128 v[166:169], v237 offset:50176
	ds_read_b128 v[170:173], v237 offset:51200
	ds_read_b128 v[174:177], v237 offset:52224
	ds_read_b128 v[178:181], v237 offset:53248
	ds_read_b128 v[182:185], v237 offset:54272
	ds_read_b128 v[186:189], v237 offset:55296
	ds_read_b128 v[210:213], v237 offset:56320
	global_load_lds_dwordx4 v202, vcc
	s_add_i32 m0, s18, 0x2000
	s_add_u32 s16, s16, 0x40080
	s_addc_u32 s17, s17, 0
	s_add_i32 s18, s77, s20
	global_load_lds_dwordx4 v198, vcc
	s_mov_b32 m0, s18
	s_nop 0
	global_load_lds_dwordx4 v202, s[16:17]
	s_add_i32 m0, s18, 0x2000
	s_nop 0
	global_load_lds_dwordx4 v198, s[16:17]
	s_mov_b32 m0, s44
	s_nop 0
	global_load_lds_dwordx4 v204, s[98:99]
	s_mov_b32 m0, s45
	s_nop 0
	global_load_lds_dwordx4 v200, s[98:99]
	s_waitcnt vmcnt(8)
	s_waitcnt lgkmcnt(0)
	s_barrier
	s_setprio 1
	s_waitcnt lgkmcnt(0)
	v_mfma_f32_16x16x32_bf16 v[62:65], v[130:133], v[162:165], v[62:65]
	v_mfma_f32_16x16x32_bf16 v[58:61], v[138:141], v[162:165], v[58:61]
	v_mfma_f32_16x16x32_bf16 v[50:53], v[130:133], v[170:173], v[50:53]
	v_mfma_f32_16x16x32_bf16 v[42:45], v[138:141], v[170:173], v[42:45]
	v_mfma_f32_16x16x32_bf16 v[34:37], v[130:133], v[178:181], v[34:37]
	v_mfma_f32_16x16x32_bf16 v[26:29], v[138:141], v[178:181], v[26:29]
	v_mfma_f32_16x16x32_bf16 v[18:21], v[130:133], v[186:189], v[18:21]
	v_mfma_f32_16x16x32_bf16 v[10:13], v[138:141], v[186:189], v[10:13]
	v_mfma_f32_16x16x32_bf16 v[62:65], v[134:137], v[166:169], v[62:65]
	v_mfma_f32_16x16x32_bf16 v[58:61], v[142:145], v[166:169], v[58:61]
	v_mfma_f32_16x16x32_bf16 v[50:53], v[134:137], v[174:177], v[50:53]
	v_mfma_f32_16x16x32_bf16 v[42:45], v[142:145], v[174:177], v[42:45]
	v_mfma_f32_16x16x32_bf16 v[34:37], v[134:137], v[182:185], v[34:37]
	v_mfma_f32_16x16x32_bf16 v[26:29], v[142:145], v[182:185], v[26:29]
	v_mfma_f32_16x16x32_bf16 v[18:21], v[134:137], v[210:213], v[18:21]
	v_mfma_f32_16x16x32_bf16 v[10:13], v[142:145], v[210:213], v[10:13]
	s_setprio 0
	s_setprio 1
	v_mfma_f32_16x16x32_bf16 v[54:57], v[146:149], v[162:165], v[54:57]
	v_mfma_f32_16x16x32_bf16 v[46:49], v[154:157], v[162:165], v[46:49]
	v_mfma_f32_16x16x32_bf16 v[38:41], v[146:149], v[170:173], v[38:41]
	v_mfma_f32_16x16x32_bf16 v[30:33], v[154:157], v[170:173], v[30:33]
	v_mfma_f32_16x16x32_bf16 v[22:25], v[146:149], v[178:181], v[22:25]
	v_mfma_f32_16x16x32_bf16 v[14:17], v[154:157], v[178:181], v[14:17]
	v_mfma_f32_16x16x32_bf16 v[6:9], v[146:149], v[186:189], v[6:9]
	v_mfma_f32_16x16x32_bf16 v[2:5], v[154:157], v[186:189], v[2:5]
	v_mfma_f32_16x16x32_bf16 v[54:57], v[150:153], v[166:169], v[54:57]
	v_mfma_f32_16x16x32_bf16 v[46:49], v[158:161], v[166:169], v[46:49]
	v_mfma_f32_16x16x32_bf16 v[38:41], v[150:153], v[174:177], v[38:41]
	v_mfma_f32_16x16x32_bf16 v[30:33], v[158:161], v[174:177], v[30:33]
	v_mfma_f32_16x16x32_bf16 v[22:25], v[150:153], v[182:185], v[22:25]
	v_mfma_f32_16x16x32_bf16 v[14:17], v[158:161], v[182:185], v[14:17]
	v_mfma_f32_16x16x32_bf16 v[6:9], v[150:153], v[210:213], v[6:9]
	v_mfma_f32_16x16x32_bf16 v[2:5], v[158:161], v[210:213], v[2:5]
	s_setprio 0
	s_barrier
	s_add_i32 s75, s75, 2
	s_add_u32 s14, s14, 0x100
	s_addc_u32 s15, s15, 0
	s_add_u32 s71, s71, 0x100
	s_addc_u32 s74, s74, 0
	s_cmp_gt_u32 s75, 13
	s_cbranch_scc0 .LBB0_1370
	s_and_b64 vcc, exec, s[4:5]
	s_mov_b64 s[74:75], 0x80000
	s_cbranch_vccz .LBB0_1373
	s_barrier
